# weight transposes: full-line (128 B contiguous per instruction) plain stores
# speedup vs baseline: 1.0119x; 1.0027x over previous
.Lptr_dec5_done:
	v_mul_lo_u32 v122, v116, s86
	v_add_u32_e32 v122, v122, v117
	s_waitcnt lgkmcnt(0)
	v_cvt_pk_bf16_f32 v104, v88, v89
	v_cvt_pk_bf16_f32 v105, v90, v91
	v_cvt_pk_bf16_f32 v106, v92, v93
	v_cvt_pk_bf16_f32 v107, v94, v95
	v_cvt_pk_bf16_f32 v108, v96, v97
	v_cvt_pk_bf16_f32 v109, v98, v99
	v_cvt_pk_bf16_f32 v110, v100, v101
	v_cvt_pk_bf16_f32 v111, v102, v103
	global_store_dwordx4 v122, v[104:107], s[74:75]
	global_store_dwordx4 v122, v[108:111], s[74:75] offset:128
	s_nop 1
	s_mul_i32 s48, s81, 4
	s_add_u32 s48, s48, s39
	s_min_u32 s48, s48, s84
	s_sub_u32 s0, s48, 0x80
	s_cmpk_lt_u32 s0, 0x80
	s_cbranch_scc1 .Lptr_dec6_br
	s_cmpk_lt_u32 s0, 0x100
	s_cbranch_scc1 .Lptr_dec6_out
	s_cmpk_lt_u32 s0, 0x3c0
	s_cbranch_scc1 .Lptr_dec6_up
	s_sub_u32 s0, s0, 0x3c0
	s_lshr_b32 s2, s0, 4
	s_and_b32 s3, s0, 15
	s_lshl_b32 s12, s2, 19
	s_lshl_b32 s13, s3, 8
	s_add_u32 s12, s12, s13
	s_add_u32 s30, s21, s12
	s_addc_u32 s31, s68, 0
	s_mul_i32 s12, s3, 0x58000
	s_lshl_b32 s13, s2, 8
	s_add_u32 s12, s12, s13
	s_add_u32 s74, s6, s12
	s_addc_u32 s75, s7, 0
	s_movk_i32 s76, 0x1000
	s_movk_i32 s86, 0x1600
	s_branch .Lptr_dec6_done

.Lptr_dec7_done:
	v_mul_lo_u32 v122, v116, s86
	v_add_u32_e32 v122, v122, v117
	s_waitcnt lgkmcnt(0)
	v_cvt_pk_bf16_f32 v104, v88, v89
	v_cvt_pk_bf16_f32 v105, v90, v91
	v_cvt_pk_bf16_f32 v106, v92, v93
	v_cvt_pk_bf16_f32 v107, v94, v95
	v_cvt_pk_bf16_f32 v108, v96, v97
	v_cvt_pk_bf16_f32 v109, v98, v99
	v_cvt_pk_bf16_f32 v110, v100, v101
	v_cvt_pk_bf16_f32 v111, v102, v103
	global_store_dwordx4 v122, v[104:107], s[74:75]
	global_store_dwordx4 v122, v[108:111], s[74:75] offset:128
	s_nop 1
	s_mul_i32 s48, s81, 5
	s_add_u32 s48, s48, s39
	s_min_u32 s48, s48, s84
	s_sub_u32 s0, s48, 0x80
	s_cmpk_lt_u32 s0, 0x80
	s_cbranch_scc1 .Lptr_dec8_br
	s_cmpk_lt_u32 s0, 0x100
	s_cbranch_scc1 .Lptr_dec8_out
	s_cmpk_lt_u32 s0, 0x3c0
	s_cbranch_scc1 .Lptr_dec8_up
	s_sub_u32 s0, s0, 0x3c0
	s_lshr_b32 s2, s0, 4
	s_and_b32 s3, s0, 15
	s_lshl_b32 s12, s2, 19
	s_lshl_b32 s13, s3, 8
	s_add_u32 s12, s12, s13
	s_add_u32 s30, s21, s12
	s_addc_u32 s31, s68, 0
	s_mul_i32 s12, s3, 0x58000
	s_lshl_b32 s13, s2, 8
	s_add_u32 s12, s12, s13
	s_add_u32 s74, s6, s12
	s_addc_u32 s75, s7, 0
	s_movk_i32 s76, 0x1000
	s_movk_i32 s86, 0x1600
	s_branch .Lptr_dec8_done

.Lptr_dec9_done:
	v_mul_lo_u32 v122, v116, s86
	v_add_u32_e32 v122, v122, v117
	s_waitcnt lgkmcnt(0)
	v_cvt_pk_bf16_f32 v104, v88, v89
	v_cvt_pk_bf16_f32 v105, v90, v91
	v_cvt_pk_bf16_f32 v106, v92, v93
	v_cvt_pk_bf16_f32 v107, v94, v95
	v_cvt_pk_bf16_f32 v108, v96, v97
	v_cvt_pk_bf16_f32 v109, v98, v99
	v_cvt_pk_bf16_f32 v110, v100, v101
	v_cvt_pk_bf16_f32 v111, v102, v103
	global_store_dwordx4 v122, v[104:107], s[74:75]
	global_store_dwordx4 v122, v[108:111], s[74:75] offset:128
	s_nop 1
	s_mul_i32 s48, s81, 6
	s_add_u32 s48, s48, s39
	s_min_u32 s48, s48, s84
	s_sub_u32 s0, s48, 0x80
	s_cmpk_lt_u32 s0, 0x80
	s_cbranch_scc1 .Lptr_dec10_br
	s_cmpk_lt_u32 s0, 0x100
	s_cbranch_scc1 .Lptr_dec10_out
	s_cmpk_lt_u32 s0, 0x3c0
	s_cbranch_scc1 .Lptr_dec10_up
	s_sub_u32 s0, s0, 0x3c0
	s_lshr_b32 s2, s0, 4
	s_and_b32 s3, s0, 15
	s_lshl_b32 s12, s2, 19
	s_lshl_b32 s13, s3, 8
	s_add_u32 s12, s12, s13
	s_add_u32 s30, s21, s12
	s_addc_u32 s31, s68, 0
	s_mul_i32 s12, s3, 0x58000
	s_lshl_b32 s13, s2, 8
	s_add_u32 s12, s12, s13
	s_add_u32 s74, s6, s12
	s_addc_u32 s75, s7, 0
	s_movk_i32 s76, 0x1000
	s_movk_i32 s86, 0x1600
	s_branch .Lptr_dec10_done

.Lptr_dec11_done:
	v_mul_lo_u32 v122, v116, s86
	v_add_u32_e32 v122, v122, v117
	s_waitcnt lgkmcnt(0)
	v_cvt_pk_bf16_f32 v104, v88, v89
	v_cvt_pk_bf16_f32 v105, v90, v91
	v_cvt_pk_bf16_f32 v106, v92, v93
	v_cvt_pk_bf16_f32 v107, v94, v95
	v_cvt_pk_bf16_f32 v108, v96, v97
	v_cvt_pk_bf16_f32 v109, v98, v99
	v_cvt_pk_bf16_f32 v110, v100, v101
	v_cvt_pk_bf16_f32 v111, v102, v103
	global_store_dwordx4 v122, v[104:107], s[74:75]
	global_store_dwordx4 v122, v[108:111], s[74:75] offset:128
	s_nop 1
	s_waitcnt vmcnt(14)
	ds_write_b32 v114, v40 offset:0
	ds_write_b32 v114, v41 offset:4
	ds_write_b32 v114, v42 offset:8
	ds_write_b32 v114, v43 offset:12
	ds_write_b32 v114, v44 offset:8320
	ds_write_b32 v114, v45 offset:8324
	ds_write_b32 v114, v46 offset:8328
	ds_write_b32 v114, v47 offset:8332
	ds_write_b32 v114, v48 offset:16640
	ds_write_b32 v114, v49 offset:16644
	ds_write_b32 v114, v50 offset:16648
	ds_write_b32 v114, v51 offset:16652
	ds_write_b32 v114, v52 offset:24960
	ds_write_b32 v114, v53 offset:24964
	ds_write_b32 v114, v54 offset:24968
	ds_write_b32 v114, v55 offset:24972
	s_waitcnt lgkmcnt(0)
	s_barrier
	ds_read_b32 v88, v115 offset:0
	ds_read_b32 v89, v115 offset:260
	ds_read_b32 v90, v115 offset:520
	ds_read_b32 v91, v115 offset:780
	ds_read_b32 v92, v115 offset:1040
	ds_read_b32 v93, v115 offset:1300
	ds_read_b32 v94, v115 offset:1560
	ds_read_b32 v95, v115 offset:1820
	ds_read_b32 v96, v115 offset:16640
	ds_read_b32 v97, v115 offset:16900
	ds_read_b32 v98, v115 offset:17160
	ds_read_b32 v99, v115 offset:17420
	ds_read_b32 v100, v115 offset:17680
	ds_read_b32 v101, v115 offset:17940
	ds_read_b32 v102, v115 offset:18200
	ds_read_b32 v103, v115 offset:18460
	s_mul_i32 s48, s81, 4
	s_add_u32 s48, s48, s39
	s_min_u32 s48, s48, s84
	s_sub_u32 s0, s48, 0x80
	s_cmpk_lt_u32 s0, 0x80
	s_cbranch_scc1 .Lptr_dec12_br
	s_cmpk_lt_u32 s0, 0x100
	s_cbranch_scc1 .Lptr_dec12_out
	s_cmpk_lt_u32 s0, 0x3c0
	s_cbranch_scc1 .Lptr_dec12_up
	s_sub_u32 s0, s0, 0x3c0
	s_lshr_b32 s2, s0, 4
	s_and_b32 s3, s0, 15
	s_lshl_b32 s12, s2, 19
	s_lshl_b32 s13, s3, 8
	s_add_u32 s12, s12, s13
	s_add_u32 s30, s21, s12
	s_addc_u32 s31, s68, 0
	s_mul_i32 s12, s3, 0x58000
	s_lshl_b32 s13, s2, 8
	s_add_u32 s12, s12, s13
	s_add_u32 s74, s6, s12
	s_addc_u32 s75, s7, 0
	s_movk_i32 s76, 0x1000
	s_movk_i32 s86, 0x1600
	s_branch .Lptr_dec12_done

.Lptr_dec12_done:
	v_mul_lo_u32 v122, v116, s86
	v_add_u32_e32 v122, v122, v117
	s_waitcnt lgkmcnt(0)
	v_cvt_pk_bf16_f32 v104, v88, v89
	v_cvt_pk_bf16_f32 v105, v90, v91
	v_cvt_pk_bf16_f32 v106, v92, v93
	v_cvt_pk_bf16_f32 v107, v94, v95
	v_cvt_pk_bf16_f32 v108, v96, v97
	v_cvt_pk_bf16_f32 v109, v98, v99
	v_cvt_pk_bf16_f32 v110, v100, v101
	v_cvt_pk_bf16_f32 v111, v102, v103
	global_store_dwordx4 v122, v[104:107], s[74:75]
	global_store_dwordx4 v122, v[108:111], s[74:75] offset:128
	s_nop 1
	s_waitcnt vmcnt(10)
	ds_write_b32 v114, v56 offset:33792
	ds_write_b32 v114, v57 offset:33796
	ds_write_b32 v114, v58 offset:33800
	ds_write_b32 v114, v59 offset:33804
	ds_write_b32 v114, v60 offset:42112
	ds_write_b32 v114, v61 offset:42116
	ds_write_b32 v114, v62 offset:42120
	ds_write_b32 v114, v63 offset:42124
	ds_write_b32 v114, v64 offset:50432
	ds_write_b32 v114, v65 offset:50436
	ds_write_b32 v114, v66 offset:50440
	ds_write_b32 v114, v67 offset:50444
	ds_write_b32 v114, v68 offset:58752
	ds_write_b32 v114, v69 offset:58756
	ds_write_b32 v114, v70 offset:58760
	ds_write_b32 v114, v71 offset:58764
	s_waitcnt lgkmcnt(0)
	s_barrier
	ds_read_b32 v88, v115 offset:33792
	ds_read_b32 v89, v115 offset:34052
	ds_read_b32 v90, v115 offset:34312
	ds_read_b32 v91, v115 offset:34572
	ds_read_b32 v92, v115 offset:34832
	ds_read_b32 v93, v115 offset:35092
	ds_read_b32 v94, v115 offset:35352
	ds_read_b32 v95, v115 offset:35612
	ds_read_b32 v96, v115 offset:50432
	ds_read_b32 v97, v115 offset:50692
	ds_read_b32 v98, v115 offset:50952
	ds_read_b32 v99, v115 offset:51212
	ds_read_b32 v100, v115 offset:51472
	ds_read_b32 v101, v115 offset:51732
	ds_read_b32 v102, v115 offset:51992
	ds_read_b32 v103, v115 offset:52252
	s_mul_i32 s48, s81, 5
	s_add_u32 s48, s48, s39
	s_min_u32 s48, s48, s84
	s_sub_u32 s0, s48, 0x80
	s_cmpk_lt_u32 s0, 0x80
	s_cbranch_scc1 .Lptr_dec13_br
	s_cmpk_lt_u32 s0, 0x100
	s_cbranch_scc1 .Lptr_dec13_out
	s_cmpk_lt_u32 s0, 0x3c0
	s_cbranch_scc1 .Lptr_dec13_up
	s_sub_u32 s0, s0, 0x3c0
	s_lshr_b32 s2, s0, 4
	s_and_b32 s3, s0, 15
	s_lshl_b32 s12, s2, 19
	s_lshl_b32 s13, s3, 8
	s_add_u32 s12, s12, s13
	s_add_u32 s30, s21, s12
	s_addc_u32 s31, s68, 0
	s_mul_i32 s12, s3, 0x58000
	s_lshl_b32 s13, s2, 8
	s_add_u32 s12, s12, s13
	s_add_u32 s74, s6, s12
	s_addc_u32 s75, s7, 0
	s_movk_i32 s76, 0x1000
	s_movk_i32 s86, 0x1600
	s_branch .Lptr_dec13_done

.Lptr_dec13_done:
	v_mul_lo_u32 v122, v116, s86
	v_add_u32_e32 v122, v122, v117
	s_waitcnt lgkmcnt(0)
	v_cvt_pk_bf16_f32 v104, v88, v89
	v_cvt_pk_bf16_f32 v105, v90, v91
	v_cvt_pk_bf16_f32 v106, v92, v93
	v_cvt_pk_bf16_f32 v107, v94, v95
	v_cvt_pk_bf16_f32 v108, v96, v97
	v_cvt_pk_bf16_f32 v109, v98, v99
	v_cvt_pk_bf16_f32 v110, v100, v101
	v_cvt_pk_bf16_f32 v111, v102, v103
	global_store_dwordx4 v122, v[104:107], s[74:75]
	global_store_dwordx4 v122, v[108:111], s[74:75] offset:128
	s_nop 1
	s_waitcnt vmcnt(6)
	ds_write_b32 v114, v72 offset:0
	ds_write_b32 v114, v73 offset:4
	ds_write_b32 v114, v74 offset:8
	ds_write_b32 v114, v75 offset:12
	ds_write_b32 v114, v76 offset:8320
	ds_write_b32 v114, v77 offset:8324
	ds_write_b32 v114, v78 offset:8328
	ds_write_b32 v114, v79 offset:8332
	ds_write_b32 v114, v80 offset:16640
	ds_write_b32 v114, v81 offset:16644
	ds_write_b32 v114, v82 offset:16648
	ds_write_b32 v114, v83 offset:16652
	ds_write_b32 v114, v84 offset:24960
	ds_write_b32 v114, v85 offset:24964
	ds_write_b32 v114, v86 offset:24968
	ds_write_b32 v114, v87 offset:24972
	s_waitcnt lgkmcnt(0)
	s_barrier
	ds_read_b32 v88, v115 offset:0
	ds_read_b32 v89, v115 offset:260
	ds_read_b32 v90, v115 offset:520
	ds_read_b32 v91, v115 offset:780
	ds_read_b32 v92, v115 offset:1040
	ds_read_b32 v93, v115 offset:1300
	ds_read_b32 v94, v115 offset:1560
	ds_read_b32 v95, v115 offset:1820
	ds_read_b32 v96, v115 offset:16640
	ds_read_b32 v97, v115 offset:16900
	ds_read_b32 v98, v115 offset:17160
	ds_read_b32 v99, v115 offset:17420
	ds_read_b32 v100, v115 offset:17680
	ds_read_b32 v101, v115 offset:17940
	ds_read_b32 v102, v115 offset:18200
	ds_read_b32 v103, v115 offset:18460
	s_mul_i32 s48, s81, 6
	s_add_u32 s48, s48, s39
	s_min_u32 s48, s48, s84
	s_sub_u32 s0, s48, 0x80
	s_cmpk_lt_u32 s0, 0x80
	s_cbranch_scc1 .Lptr_dec14_br
	s_cmpk_lt_u32 s0, 0x100
	s_cbranch_scc1 .Lptr_dec14_out
	s_cmpk_lt_u32 s0, 0x3c0
	s_cbranch_scc1 .Lptr_dec14_up
	s_sub_u32 s0, s0, 0x3c0
	s_lshr_b32 s2, s0, 4
	s_and_b32 s3, s0, 15
	s_lshl_b32 s12, s2, 19
	s_lshl_b32 s13, s3, 8
	s_add_u32 s12, s12, s13
	s_add_u32 s30, s21, s12
	s_addc_u32 s31, s68, 0
	s_mul_i32 s12, s3, 0x58000
	s_lshl_b32 s13, s2, 8
	s_add_u32 s12, s12, s13
	s_add_u32 s74, s6, s12
	s_addc_u32 s75, s7, 0
	s_movk_i32 s76, 0x1000
	s_movk_i32 s86, 0x1600
	s_branch .Lptr_dec14_done

.Lptr_dec14_done:
	v_mul_lo_u32 v122, v116, s86
	v_add_u32_e32 v122, v122, v117
	s_waitcnt lgkmcnt(0)
	v_cvt_pk_bf16_f32 v104, v88, v89
	v_cvt_pk_bf16_f32 v105, v90, v91
	v_cvt_pk_bf16_f32 v106, v92, v93
	v_cvt_pk_bf16_f32 v107, v94, v95
	v_cvt_pk_bf16_f32 v108, v96, v97
	v_cvt_pk_bf16_f32 v109, v98, v99
	v_cvt_pk_bf16_f32 v110, v100, v101
	v_cvt_pk_bf16_f32 v111, v102, v103
	global_store_dwordx4 v122, v[104:107], s[74:75]
	global_store_dwordx4 v122, v[108:111], s[74:75] offset:128
	s_nop 1
	s_waitcnt vmcnt(0)
	s_barrier
	s_branch .LBB0_602

.Ln1t_kdone:
	v_lshrrev_b32_e32 v112, 4, v1
	v_and_b32_e32 v113, 15, v1
	v_lshlrev_b32_e32 v113, 4, v113
	v_mul_u32_u24_e32 v114, 0x104, v112
	v_add_u32_e32 v114, v114, v113
	v_lshrrev_b32_e32 v116, 3, v1
	v_and_b32_e32 v117, 7, v1
	v_mul_u32_u24_e32 v115, 0x820, v117
	v_lshl_add_u32 v115, v116, 2, v115
	v_lshlrev_b32_e32 v117, 4, v117
	s_mul_i32 s48, s73, 0
	s_add_u32 s48, s48, s74
	s_min_u32 s48, s48, s72
	s_mov_b32 s0, s48
	s_mul_i32 s2, s0, 0x4ed
	s_lshr_b32 s2, s2, 17
	s_mul_i32 s3, s2, 0x68
	s_sub_u32 s3, s0, s3
	s_mul_i32 s14, s2, 0x340000
	s_lshl_b32 s0, s3, 8
	s_add_u32 s14, s14, s0
	s_add_u32 s6, s68, s14
	s_addc_u32 s7, s69, 0
	s_lshl_b32 s14, s3, 17
	s_lshl_b32 s0, s2, 8
	s_add_u32 s14, s14, s0
	s_add_u32 s8, s70, s14
	s_addc_u32 s9, s71, 0
	s_movk_i32 s12, 0x6800
	s_movk_i32 s13, 0x800
	v_mul_lo_u32 v123, v112, s12
	v_add_u32_e32 v118, v123, v113
	s_lshl_b32 vcc_lo, s12, 5
	v_add_u32_e32 v119, vcc_lo, v118
	v_add_u32_e32 v120, vcc_lo, v119
	v_add_u32_e32 v121, vcc_lo, v120
	global_load_dwordx4 v[40:43], v118, s[6:7] nt
	global_load_dwordx4 v[44:47], v119, s[6:7] nt
	global_load_dwordx4 v[48:51], v120, s[6:7] nt
	global_load_dwordx4 v[52:55], v121, s[6:7] nt
	s_mul_i32 s48, s73, 1
	s_add_u32 s48, s48, s74
	s_min_u32 s48, s48, s72
	s_mov_b32 s0, s48
	s_mul_i32 s2, s0, 0x4ed
	s_lshr_b32 s2, s2, 17
	s_mul_i32 s3, s2, 0x68
	s_sub_u32 s3, s0, s3
	s_mul_i32 s14, s2, 0x340000
	s_lshl_b32 s0, s3, 8
	s_add_u32 s14, s14, s0
	s_add_u32 s6, s68, s14
	s_addc_u32 s7, s69, 0
	s_lshl_b32 s14, s3, 17
	s_lshl_b32 s0, s2, 8
	s_add_u32 s14, s14, s0
	s_add_u32 s8, s70, s14
	s_addc_u32 s9, s71, 0
	s_movk_i32 s12, 0x6800
	s_movk_i32 s13, 0x800
	v_mul_lo_u32 v123, v112, s12
	v_add_u32_e32 v118, v123, v113
	s_lshl_b32 vcc_lo, s12, 5
	v_add_u32_e32 v119, vcc_lo, v118
	v_add_u32_e32 v120, vcc_lo, v119
	v_add_u32_e32 v121, vcc_lo, v120
	global_load_dwordx4 v[56:59], v118, s[6:7] nt
	global_load_dwordx4 v[60:63], v119, s[6:7] nt
	global_load_dwordx4 v[64:67], v120, s[6:7] nt
	global_load_dwordx4 v[68:71], v121, s[6:7] nt
	s_waitcnt vmcnt(4)
	ds_write_b32 v114, v40 offset:0
	ds_write_b32 v114, v41 offset:4
	ds_write_b32 v114, v42 offset:8
	ds_write_b32 v114, v43 offset:12
	ds_write_b32 v114, v44 offset:8320
	ds_write_b32 v114, v45 offset:8324
	ds_write_b32 v114, v46 offset:8328
	ds_write_b32 v114, v47 offset:8332
	ds_write_b32 v114, v48 offset:16640
	ds_write_b32 v114, v49 offset:16644
	ds_write_b32 v114, v50 offset:16648
	ds_write_b32 v114, v51 offset:16652
	ds_write_b32 v114, v52 offset:24960
	ds_write_b32 v114, v53 offset:24964
	ds_write_b32 v114, v54 offset:24968
	ds_write_b32 v114, v55 offset:24972
	s_waitcnt lgkmcnt(0)
	s_barrier
	ds_read_b32 v88, v115 offset:0
	ds_read_b32 v89, v115 offset:260
	ds_read_b32 v90, v115 offset:520
	ds_read_b32 v91, v115 offset:780
	ds_read_b32 v92, v115 offset:1040
	ds_read_b32 v93, v115 offset:1300
	ds_read_b32 v94, v115 offset:1560
	ds_read_b32 v95, v115 offset:1820
	ds_read_b32 v96, v115 offset:16640
	ds_read_b32 v97, v115 offset:16900
	ds_read_b32 v98, v115 offset:17160
	ds_read_b32 v99, v115 offset:17420
	ds_read_b32 v100, v115 offset:17680
	ds_read_b32 v101, v115 offset:17940
	ds_read_b32 v102, v115 offset:18200
	ds_read_b32 v103, v115 offset:18460
	s_mul_i32 s48, s73, 0
	s_add_u32 s48, s48, s74
	s_min_u32 s48, s48, s72
	s_mov_b32 s0, s48
	s_mul_i32 s2, s0, 0x4ed
	s_lshr_b32 s2, s2, 17
	s_mul_i32 s3, s2, 0x68
	s_sub_u32 s3, s0, s3
	s_mul_i32 s14, s2, 0x340000
	s_lshl_b32 s0, s3, 8
	s_add_u32 s14, s14, s0
	s_add_u32 s6, s68, s14
	s_addc_u32 s7, s69, 0
	s_lshl_b32 s14, s3, 17
	s_lshl_b32 s0, s2, 8
	s_add_u32 s14, s14, s0
	s_add_u32 s8, s70, s14
	s_addc_u32 s9, s71, 0
	s_movk_i32 s12, 0x6800
	s_movk_i32 s13, 0x800
	v_mul_lo_u32 v122, v116, s13
	v_add_u32_e32 v122, v122, v117
	s_waitcnt lgkmcnt(0)
	v_cvt_pk_bf16_f32 v104, v88, v89
	v_cvt_pk_bf16_f32 v105, v90, v91
	v_cvt_pk_bf16_f32 v106, v92, v93
	v_cvt_pk_bf16_f32 v107, v94, v95
	v_cvt_pk_bf16_f32 v108, v96, v97
	v_cvt_pk_bf16_f32 v109, v98, v99
	v_cvt_pk_bf16_f32 v110, v100, v101
	v_cvt_pk_bf16_f32 v111, v102, v103
	global_store_dwordx4 v122, v[104:107], s[8:9]
	global_store_dwordx4 v122, v[108:111], s[8:9] offset:128
	s_nop 1
	s_waitcnt vmcnt(2)
	ds_write_b32 v114, v56 offset:33792
	ds_write_b32 v114, v57 offset:33796
	ds_write_b32 v114, v58 offset:33800
	ds_write_b32 v114, v59 offset:33804
	ds_write_b32 v114, v60 offset:42112
	ds_write_b32 v114, v61 offset:42116
	ds_write_b32 v114, v62 offset:42120
	ds_write_b32 v114, v63 offset:42124
	ds_write_b32 v114, v64 offset:50432
	ds_write_b32 v114, v65 offset:50436
	ds_write_b32 v114, v66 offset:50440
	ds_write_b32 v114, v67 offset:50444
	ds_write_b32 v114, v68 offset:58752
	ds_write_b32 v114, v69 offset:58756
	ds_write_b32 v114, v70 offset:58760
	ds_write_b32 v114, v71 offset:58764
	s_waitcnt lgkmcnt(0)
	s_barrier
	ds_read_b32 v88, v115 offset:33792
	ds_read_b32 v89, v115 offset:34052
	ds_read_b32 v90, v115 offset:34312
	ds_read_b32 v91, v115 offset:34572
	ds_read_b32 v92, v115 offset:34832
	ds_read_b32 v93, v115 offset:35092
	ds_read_b32 v94, v115 offset:35352
	ds_read_b32 v95, v115 offset:35612
	ds_read_b32 v96, v115 offset:50432
	ds_read_b32 v97, v115 offset:50692
	ds_read_b32 v98, v115 offset:50952
	ds_read_b32 v99, v115 offset:51212
	ds_read_b32 v100, v115 offset:51472
	ds_read_b32 v101, v115 offset:51732
	ds_read_b32 v102, v115 offset:51992
	ds_read_b32 v103, v115 offset:52252
	s_mul_i32 s48, s73, 1
	s_add_u32 s48, s48, s74
	s_min_u32 s48, s48, s72
	s_mov_b32 s0, s48
	s_mul_i32 s2, s0, 0x4ed
	s_lshr_b32 s2, s2, 17
	s_mul_i32 s3, s2, 0x68
	s_sub_u32 s3, s0, s3
	s_mul_i32 s14, s2, 0x340000
	s_lshl_b32 s0, s3, 8
	s_add_u32 s14, s14, s0
	s_add_u32 s6, s68, s14
	s_addc_u32 s7, s69, 0
	s_lshl_b32 s14, s3, 17
	s_lshl_b32 s0, s2, 8
	s_add_u32 s14, s14, s0
	s_add_u32 s8, s70, s14
	s_addc_u32 s9, s71, 0
	s_movk_i32 s12, 0x6800
	s_movk_i32 s13, 0x800
	v_mul_lo_u32 v122, v116, s13
	v_add_u32_e32 v122, v122, v117
	s_waitcnt lgkmcnt(0)
	v_cvt_pk_bf16_f32 v104, v88, v89
	v_cvt_pk_bf16_f32 v105, v90, v91
	v_cvt_pk_bf16_f32 v106, v92, v93
	v_cvt_pk_bf16_f32 v107, v94, v95
	v_cvt_pk_bf16_f32 v108, v96, v97
	v_cvt_pk_bf16_f32 v109, v98, v99
	v_cvt_pk_bf16_f32 v110, v100, v101
	v_cvt_pk_bf16_f32 v111, v102, v103
	global_store_dwordx4 v122, v[104:107], s[8:9]
	global_store_dwordx4 v122, v[108:111], s[8:9] offset:128
	s_nop 1
	s_waitcnt vmcnt(0)
	s_barrier
	s_branch .LBB0_692

.Lp0t_kdone:
	v_lshrrev_b32_e32 v112, 4, v1
	v_and_b32_e32 v113, 15, v1
	v_lshlrev_b32_e32 v113, 4, v113
	v_mul_u32_u24_e32 v114, 0x104, v112
	v_add_u32_e32 v114, v114, v113
	v_lshrrev_b32_e32 v116, 3, v1
	v_and_b32_e32 v117, 7, v1
	v_mul_u32_u24_e32 v115, 0x820, v117
	v_lshl_add_u32 v115, v116, 2, v115
	v_lshlrev_b32_e32 v117, 4, v117
	s_mul_i32 s48, s85, 0
	s_add_u32 s48, s48, s86
	s_min_u32 s48, s48, s84
	s_sub_u32 s0, s48, 0xe0
	s_mul_i32 s2, s0, 0x4ed
	s_lshr_b32 s2, s2, 17
	s_mul_i32 s3, s2, 0x68
	s_sub_u32 s3, s0, s3
	s_mul_i32 s4, s2, 0x340000
	s_lshl_b32 s0, s3, 8
	s_add_u32 s4, s4, s0
	s_add_u32 s6, s80, s4
	s_addc_u32 s7, s81, 0
	s_lshl_b32 s4, s3, 17
	s_lshl_b32 s0, s2, 8
	s_add_u32 s4, s4, s0
	s_add_u32 s8, s82, s4
	s_addc_u32 s9, s83, 0
	s_movk_i32 s10, 0x6800
	s_movk_i32 s11, 0x800
	v_mul_lo_u32 v123, v112, s10
	v_add_u32_e32 v118, v123, v113
	s_lshl_b32 vcc_lo, s10, 5
	v_add_u32_e32 v119, vcc_lo, v118
	v_add_u32_e32 v120, vcc_lo, v119
	v_add_u32_e32 v121, vcc_lo, v120
	global_load_dwordx4 v[40:43], v118, s[6:7] nt
	global_load_dwordx4 v[44:47], v119, s[6:7] nt
	global_load_dwordx4 v[48:51], v120, s[6:7] nt
	global_load_dwordx4 v[52:55], v121, s[6:7] nt
	s_mul_i32 s48, s85, 1
	s_add_u32 s48, s48, s86
	s_min_u32 s48, s48, s84
	s_sub_u32 s0, s48, 0xe0
	s_mul_i32 s2, s0, 0x4ed
	s_lshr_b32 s2, s2, 17
	s_mul_i32 s3, s2, 0x68
	s_sub_u32 s3, s0, s3
	s_mul_i32 s4, s2, 0x340000
	s_lshl_b32 s0, s3, 8
	s_add_u32 s4, s4, s0
	s_add_u32 s6, s80, s4
	s_addc_u32 s7, s81, 0
	s_lshl_b32 s4, s3, 17
	s_lshl_b32 s0, s2, 8
	s_add_u32 s4, s4, s0
	s_add_u32 s8, s82, s4
	s_addc_u32 s9, s83, 0
	s_movk_i32 s10, 0x6800
	s_movk_i32 s11, 0x800
	v_mul_lo_u32 v123, v112, s10
	v_add_u32_e32 v118, v123, v113
	s_lshl_b32 vcc_lo, s10, 5
	v_add_u32_e32 v119, vcc_lo, v118
	v_add_u32_e32 v120, vcc_lo, v119
	v_add_u32_e32 v121, vcc_lo, v120
	global_load_dwordx4 v[56:59], v118, s[6:7] nt
	global_load_dwordx4 v[60:63], v119, s[6:7] nt
	global_load_dwordx4 v[64:67], v120, s[6:7] nt
	global_load_dwordx4 v[68:71], v121, s[6:7] nt
	s_mul_i32 s48, s85, 2
	s_add_u32 s48, s48, s86
	s_min_u32 s48, s48, s84
	s_sub_u32 s0, s48, 0xe0
	s_mul_i32 s2, s0, 0x4ed
	s_lshr_b32 s2, s2, 17
	s_mul_i32 s3, s2, 0x68
	s_sub_u32 s3, s0, s3
	s_mul_i32 s4, s2, 0x340000
	s_lshl_b32 s0, s3, 8
	s_add_u32 s4, s4, s0
	s_add_u32 s6, s80, s4
	s_addc_u32 s7, s81, 0
	s_lshl_b32 s4, s3, 17
	s_lshl_b32 s0, s2, 8
	s_add_u32 s4, s4, s0
	s_add_u32 s8, s82, s4
	s_addc_u32 s9, s83, 0
	s_movk_i32 s10, 0x6800
	s_movk_i32 s11, 0x800
	v_mul_lo_u32 v123, v112, s10
	v_add_u32_e32 v118, v123, v113
	s_lshl_b32 vcc_lo, s10, 5
	v_add_u32_e32 v119, vcc_lo, v118
	v_add_u32_e32 v120, vcc_lo, v119
	v_add_u32_e32 v121, vcc_lo, v120
	global_load_dwordx4 v[72:75], v118, s[6:7] nt
	global_load_dwordx4 v[76:79], v119, s[6:7] nt
	global_load_dwordx4 v[80:83], v120, s[6:7] nt
	global_load_dwordx4 v[84:87], v121, s[6:7] nt
	s_mul_i32 s48, s85, 3
	s_add_u32 s48, s48, s86
	s_min_u32 s48, s48, s84
	s_sub_u32 s0, s48, 0xe0
	s_mul_i32 s2, s0, 0x4ed
	s_lshr_b32 s2, s2, 17
	s_mul_i32 s3, s2, 0x68
	s_sub_u32 s3, s0, s3
	s_mul_i32 s4, s2, 0x340000
	s_lshl_b32 s0, s3, 8
	s_add_u32 s4, s4, s0
	s_add_u32 s6, s80, s4
	s_addc_u32 s7, s81, 0
	s_lshl_b32 s4, s3, 17
	s_lshl_b32 s0, s2, 8
	s_add_u32 s4, s4, s0
	s_add_u32 s8, s82, s4
	s_addc_u32 s9, s83, 0
	s_movk_i32 s10, 0x6800
	s_movk_i32 s11, 0x800
	v_mul_lo_u32 v123, v112, s10
	v_add_u32_e32 v118, v123, v113
	s_lshl_b32 vcc_lo, s10, 5
	v_add_u32_e32 v119, vcc_lo, v118
	v_add_u32_e32 v120, vcc_lo, v119
	v_add_u32_e32 v121, vcc_lo, v120
	global_load_dwordx4 v[124:127], v118, s[6:7] nt
	global_load_dwordx4 v[128:131], v119, s[6:7] nt
	global_load_dwordx4 v[132:135], v120, s[6:7] nt
	global_load_dwordx4 v[136:139], v121, s[6:7] nt
	s_waitcnt vmcnt(12)
	ds_write_b32 v114, v40 offset:0
	ds_write_b32 v114, v41 offset:4
	ds_write_b32 v114, v42 offset:8
	ds_write_b32 v114, v43 offset:12
	ds_write_b32 v114, v44 offset:8320
	ds_write_b32 v114, v45 offset:8324
	ds_write_b32 v114, v46 offset:8328
	ds_write_b32 v114, v47 offset:8332
	ds_write_b32 v114, v48 offset:16640
	ds_write_b32 v114, v49 offset:16644
	ds_write_b32 v114, v50 offset:16648
	ds_write_b32 v114, v51 offset:16652
	ds_write_b32 v114, v52 offset:24960
	ds_write_b32 v114, v53 offset:24964
	ds_write_b32 v114, v54 offset:24968
	ds_write_b32 v114, v55 offset:24972
	s_waitcnt lgkmcnt(0)
	s_barrier
	ds_read_b32 v88, v115 offset:0
	ds_read_b32 v89, v115 offset:260
	ds_read_b32 v90, v115 offset:520
	ds_read_b32 v91, v115 offset:780
	ds_read_b32 v92, v115 offset:1040
	ds_read_b32 v93, v115 offset:1300
	ds_read_b32 v94, v115 offset:1560
	ds_read_b32 v95, v115 offset:1820
	ds_read_b32 v96, v115 offset:16640
	ds_read_b32 v97, v115 offset:16900
	ds_read_b32 v98, v115 offset:17160
	ds_read_b32 v99, v115 offset:17420
	ds_read_b32 v100, v115 offset:17680
	ds_read_b32 v101, v115 offset:17940
	ds_read_b32 v102, v115 offset:18200
	ds_read_b32 v103, v115 offset:18460
	s_mul_i32 s48, s85, 0
	s_add_u32 s48, s48, s86
	s_min_u32 s48, s48, s84
	s_sub_u32 s0, s48, 0xe0
	s_mul_i32 s2, s0, 0x4ed
	s_lshr_b32 s2, s2, 17
	s_mul_i32 s3, s2, 0x68
	s_sub_u32 s3, s0, s3
	s_mul_i32 s4, s2, 0x340000
	s_lshl_b32 s0, s3, 8
	s_add_u32 s4, s4, s0
	s_add_u32 s6, s80, s4
	s_addc_u32 s7, s81, 0
	s_lshl_b32 s4, s3, 17
	s_lshl_b32 s0, s2, 8
	s_add_u32 s4, s4, s0
	s_add_u32 s8, s82, s4
	s_addc_u32 s9, s83, 0
	s_movk_i32 s10, 0x6800
	s_movk_i32 s11, 0x800
	v_mul_lo_u32 v122, v116, s11
	v_add_u32_e32 v122, v122, v117
	s_waitcnt lgkmcnt(0)
	v_cvt_pk_bf16_f32 v104, v88, v89
	v_cvt_pk_bf16_f32 v105, v90, v91
	v_cvt_pk_bf16_f32 v106, v92, v93
	v_cvt_pk_bf16_f32 v107, v94, v95
	v_cvt_pk_bf16_f32 v108, v96, v97
	v_cvt_pk_bf16_f32 v109, v98, v99
	v_cvt_pk_bf16_f32 v110, v100, v101
	v_cvt_pk_bf16_f32 v111, v102, v103
	global_store_dwordx4 v122, v[104:107], s[8:9]
	global_store_dwordx4 v122, v[108:111], s[8:9] offset:128
	s_nop 1
	s_waitcnt vmcnt(10)
	ds_write_b32 v114, v56 offset:33792
	ds_write_b32 v114, v57 offset:33796
	ds_write_b32 v114, v58 offset:33800
	ds_write_b32 v114, v59 offset:33804
	ds_write_b32 v114, v60 offset:42112
	ds_write_b32 v114, v61 offset:42116
	ds_write_b32 v114, v62 offset:42120
	ds_write_b32 v114, v63 offset:42124
	ds_write_b32 v114, v64 offset:50432
	ds_write_b32 v114, v65 offset:50436
	ds_write_b32 v114, v66 offset:50440
	ds_write_b32 v114, v67 offset:50444
	ds_write_b32 v114, v68 offset:58752
	ds_write_b32 v114, v69 offset:58756
	ds_write_b32 v114, v70 offset:58760
	ds_write_b32 v114, v71 offset:58764
	s_waitcnt lgkmcnt(0)
	s_barrier
	ds_read_b32 v88, v115 offset:33792
	ds_read_b32 v89, v115 offset:34052
	ds_read_b32 v90, v115 offset:34312
	ds_read_b32 v91, v115 offset:34572
	ds_read_b32 v92, v115 offset:34832
	ds_read_b32 v93, v115 offset:35092
	ds_read_b32 v94, v115 offset:35352
	ds_read_b32 v95, v115 offset:35612
	ds_read_b32 v96, v115 offset:50432
	ds_read_b32 v97, v115 offset:50692
	ds_read_b32 v98, v115 offset:50952
	ds_read_b32 v99, v115 offset:51212
	ds_read_b32 v100, v115 offset:51472
	ds_read_b32 v101, v115 offset:51732
	ds_read_b32 v102, v115 offset:51992
	ds_read_b32 v103, v115 offset:52252
	s_mul_i32 s48, s85, 1
	s_add_u32 s48, s48, s86
	s_min_u32 s48, s48, s84
	s_sub_u32 s0, s48, 0xe0
	s_mul_i32 s2, s0, 0x4ed
	s_lshr_b32 s2, s2, 17
	s_mul_i32 s3, s2, 0x68
	s_sub_u32 s3, s0, s3
	s_mul_i32 s4, s2, 0x340000
	s_lshl_b32 s0, s3, 8
	s_add_u32 s4, s4, s0
	s_add_u32 s6, s80, s4
	s_addc_u32 s7, s81, 0
	s_lshl_b32 s4, s3, 17
	s_lshl_b32 s0, s2, 8
	s_add_u32 s4, s4, s0
	s_add_u32 s8, s82, s4
	s_addc_u32 s9, s83, 0
	s_movk_i32 s10, 0x6800
	s_movk_i32 s11, 0x800
	v_mul_lo_u32 v122, v116, s11
	v_add_u32_e32 v122, v122, v117
	s_waitcnt lgkmcnt(0)
	v_cvt_pk_bf16_f32 v104, v88, v89
	v_cvt_pk_bf16_f32 v105, v90, v91
	v_cvt_pk_bf16_f32 v106, v92, v93
	v_cvt_pk_bf16_f32 v107, v94, v95
	v_cvt_pk_bf16_f32 v108, v96, v97
	v_cvt_pk_bf16_f32 v109, v98, v99
	v_cvt_pk_bf16_f32 v110, v100, v101
	v_cvt_pk_bf16_f32 v111, v102, v103
	global_store_dwordx4 v122, v[104:107], s[8:9]
	global_store_dwordx4 v122, v[108:111], s[8:9] offset:128
	s_nop 1
	s_waitcnt vmcnt(8)
	ds_write_b32 v114, v72 offset:0
	ds_write_b32 v114, v73 offset:4
	ds_write_b32 v114, v74 offset:8
	ds_write_b32 v114, v75 offset:12
	ds_write_b32 v114, v76 offset:8320
	ds_write_b32 v114, v77 offset:8324
	ds_write_b32 v114, v78 offset:8328
	ds_write_b32 v114, v79 offset:8332
	ds_write_b32 v114, v80 offset:16640
	ds_write_b32 v114, v81 offset:16644
	ds_write_b32 v114, v82 offset:16648
	ds_write_b32 v114, v83 offset:16652
	ds_write_b32 v114, v84 offset:24960
	ds_write_b32 v114, v85 offset:24964
	ds_write_b32 v114, v86 offset:24968
	ds_write_b32 v114, v87 offset:24972
	s_waitcnt lgkmcnt(0)
	s_barrier
	ds_read_b32 v88, v115 offset:0
	ds_read_b32 v89, v115 offset:260
	ds_read_b32 v90, v115 offset:520
	ds_read_b32 v91, v115 offset:780
	ds_read_b32 v92, v115 offset:1040
	ds_read_b32 v93, v115 offset:1300
	ds_read_b32 v94, v115 offset:1560
	ds_read_b32 v95, v115 offset:1820
	ds_read_b32 v96, v115 offset:16640
	ds_read_b32 v97, v115 offset:16900
	ds_read_b32 v98, v115 offset:17160
	ds_read_b32 v99, v115 offset:17420
	ds_read_b32 v100, v115 offset:17680
	ds_read_b32 v101, v115 offset:17940
	ds_read_b32 v102, v115 offset:18200
	ds_read_b32 v103, v115 offset:18460
	s_mul_i32 s48, s85, 2
	s_add_u32 s48, s48, s86
	s_min_u32 s48, s48, s84
	s_sub_u32 s0, s48, 0xe0
	s_mul_i32 s2, s0, 0x4ed
	s_lshr_b32 s2, s2, 17
	s_mul_i32 s3, s2, 0x68
	s_sub_u32 s3, s0, s3
	s_mul_i32 s4, s2, 0x340000
	s_lshl_b32 s0, s3, 8
	s_add_u32 s4, s4, s0
	s_add_u32 s6, s80, s4
	s_addc_u32 s7, s81, 0
	s_lshl_b32 s4, s3, 17
	s_lshl_b32 s0, s2, 8
	s_add_u32 s4, s4, s0
	s_add_u32 s8, s82, s4
	s_addc_u32 s9, s83, 0
	s_movk_i32 s10, 0x6800
	s_movk_i32 s11, 0x800
	v_mul_lo_u32 v122, v116, s11
	v_add_u32_e32 v122, v122, v117
	s_waitcnt lgkmcnt(0)
	v_cvt_pk_bf16_f32 v104, v88, v89
	v_cvt_pk_bf16_f32 v105, v90, v91
	v_cvt_pk_bf16_f32 v106, v92, v93
	v_cvt_pk_bf16_f32 v107, v94, v95
	v_cvt_pk_bf16_f32 v108, v96, v97
	v_cvt_pk_bf16_f32 v109, v98, v99
	v_cvt_pk_bf16_f32 v110, v100, v101
	v_cvt_pk_bf16_f32 v111, v102, v103
	global_store_dwordx4 v122, v[104:107], s[8:9]
	global_store_dwordx4 v122, v[108:111], s[8:9] offset:128
	s_nop 1
	s_waitcnt vmcnt(6)
	ds_write_b32 v114, v124 offset:33792
	ds_write_b32 v114, v125 offset:33796
	ds_write_b32 v114, v126 offset:33800
	ds_write_b32 v114, v127 offset:33804
	ds_write_b32 v114, v128 offset:42112
	ds_write_b32 v114, v129 offset:42116
	ds_write_b32 v114, v130 offset:42120
	ds_write_b32 v114, v131 offset:42124
	ds_write_b32 v114, v132 offset:50432
	ds_write_b32 v114, v133 offset:50436
	ds_write_b32 v114, v134 offset:50440
	ds_write_b32 v114, v135 offset:50444
	ds_write_b32 v114, v136 offset:58752
	ds_write_b32 v114, v137 offset:58756
	ds_write_b32 v114, v138 offset:58760
	ds_write_b32 v114, v139 offset:58764
	s_waitcnt lgkmcnt(0)
	s_barrier
	ds_read_b32 v88, v115 offset:33792
	ds_read_b32 v89, v115 offset:34052
	ds_read_b32 v90, v115 offset:34312
	ds_read_b32 v91, v115 offset:34572
	ds_read_b32 v92, v115 offset:34832
	ds_read_b32 v93, v115 offset:35092
	ds_read_b32 v94, v115 offset:35352
	ds_read_b32 v95, v115 offset:35612
	ds_read_b32 v96, v115 offset:50432
	ds_read_b32 v97, v115 offset:50692
	ds_read_b32 v98, v115 offset:50952
	ds_read_b32 v99, v115 offset:51212
	ds_read_b32 v100, v115 offset:51472
	ds_read_b32 v101, v115 offset:51732
	ds_read_b32 v102, v115 offset:51992
	ds_read_b32 v103, v115 offset:52252
	s_mul_i32 s48, s85, 3
	s_add_u32 s48, s48, s86
	s_min_u32 s48, s48, s84
	s_sub_u32 s0, s48, 0xe0
	s_mul_i32 s2, s0, 0x4ed
	s_lshr_b32 s2, s2, 17
	s_mul_i32 s3, s2, 0x68
	s_sub_u32 s3, s0, s3
	s_mul_i32 s4, s2, 0x340000
	s_lshl_b32 s0, s3, 8
	s_add_u32 s4, s4, s0
	s_add_u32 s6, s80, s4
	s_addc_u32 s7, s81, 0
	s_lshl_b32 s4, s3, 17
	s_lshl_b32 s0, s2, 8
	s_add_u32 s4, s4, s0
	s_add_u32 s8, s82, s4
	s_addc_u32 s9, s83, 0
	s_movk_i32 s10, 0x6800
	s_movk_i32 s11, 0x800
	v_mul_lo_u32 v122, v116, s11
	v_add_u32_e32 v122, v122, v117
	s_waitcnt lgkmcnt(0)
	v_cvt_pk_bf16_f32 v104, v88, v89
	v_cvt_pk_bf16_f32 v105, v90, v91
	v_cvt_pk_bf16_f32 v106, v92, v93
	v_cvt_pk_bf16_f32 v107, v94, v95
	v_cvt_pk_bf16_f32 v108, v96, v97
	v_cvt_pk_bf16_f32 v109, v98, v99
	v_cvt_pk_bf16_f32 v110, v100, v101
	v_cvt_pk_bf16_f32 v111, v102, v103
	global_store_dwordx4 v122, v[104:107], s[8:9]
	global_store_dwordx4 v122, v[108:111], s[8:9] offset:128
	s_nop 1
	s_waitcnt vmcnt(0)
	s_barrier
	s_branch .LBB0_726
